# peeled-first-iteration kernel plus epilogue load latency: out-proj epilogue issues half of the second residual batch with the first batch into dead fragment VGPRs, FFN-in rstd block issues both partia
# baseline (speedup 1.0000x reference)
; __device__ __forceinline__ float rstd_row(const u64_t* ssp, int row) {
;     const f32x4* p = (const f32x4*)(ssp + (size_t)row * 16);
;     const f32x4 a = p[0], b = p[1], c = p[2], d = p[3];
;     const f32x4 s = (a + b) + (c + d);
;     const float t = (s[0] + s[1]) + (s[2] + s[3]);
;     return __builtin_amdgcn_rsqf(t * (1.0f / 1024.0f) + RMS_EPS_F);
; }
;     __device__ __forceinline__ void refresh(const u64_t* ssq, int pm, int wr, int fr, int fq) const {
;         if (pm != cpm) {
;             cpm = pm;
;             const int lane = fr + 16 * fq;
; #pragma unroll
;             for (int h = 0; h < 2; ++h) { const int idx = lane + 64 * h, am = idx >> 4, f = idx & 15;
;                 tab[idx] = rstd_row(ssq, pm * BM + (am >> 2) * HALF + wr * 64 + (am & 3) * 16 + f); }
.LBB0_113:
	s_lshl_b32 s15, s61, 8
	s_add_i32 s15, s15, s54
	v_mov_b32_e32 v145, v81
	v_mov_b32_e32 v147, v142
	s_cmp_eq_u32 s61, s59
	v_readlane_b32 s64, v248, 33
	s_cbranch_scc1 .LBB0_115
	v_lshl_add_u32 v146, v147, 4, v145
	v_and_b32_e32 v148, 15, v145
	v_and_b32_e32 v149, 48, v146
	v_lshlrev_b32_e32 v181, 1, v146
	v_or3_b32 v180, v148, v149, s15
	v_and_b32_e32 v148, 0xffffff80, v181
	v_add_u32_e32 v148, v180, v148
	v_ashrrev_i32_e32 v149, 31, v148
	v_lshlrev_b64 v[148:149], 6, v[148:149]
	v_lshl_add_u64 v[160:161], s[26:27], 0, v[148:149]
	global_load_dwordx4 v[148:151], v[160:161], off offset:32
	global_load_dwordx4 v[152:155], v[160:161], off offset:48
	global_load_dwordx4 v[156:159], v[160:161], off
	global_load_dwordx4 v[176:179], v[160:161], off offset:16
	v_add_u32_e32 v184, 0x80, v181
	v_and_b32_e32 v184, 0xffffff80, v184
	v_add_u32_e32 v184, v180, v184
	v_ashrrev_i32_e32 v185, 31, v184
	v_lshlrev_b64 v[184:185], 6, v[184:185]
	v_lshl_add_u64 v[184:185], s[26:27], 0, v[184:185]
	global_load_dwordx4 v[208:211], v[184:185], off offset:32
	global_load_dwordx4 v[212:215], v[184:185], off offset:48
	global_load_dwordx4 v[216:219], v[184:185], off
	global_load_dwordx4 v[220:223], v[184:185], off offset:16
	v_lshl_add_u32 v146, v146, 2, s3
	s_mov_b32 s59, s61
	s_waitcnt vmcnt(0)
	v_pk_add_f32 v[150:151], v[150:151], v[154:155]
	v_pk_add_f32 v[148:149], v[148:149], v[152:153]
	v_pk_add_f32 v[158:159], v[158:159], v[178:179]
	v_pk_add_f32 v[156:157], v[156:157], v[176:177]
	v_pk_add_f32 v[150:151], v[158:159], v[150:151]
	v_pk_add_f32 v[148:149], v[156:157], v[148:149]
	s_nop 0
	v_add_f32_e32 v148, v148, v149
	v_add_f32_e32 v149, v150, v151
	v_add_f32_e32 v148, v148, v149
	v_fmamk_f32 v148, v148, 0x3a800000, v205
	v_rsq_f32_e32 v182, v148
	v_add_u32_e32 v148, 0x80, v181
	v_and_b32_e32 v148, 0xffffff80, v148
	v_add_u32_e32 v148, v180, v148
	v_ashrrev_i32_e32 v149, 31, v148
	v_lshlrev_b64 v[148:149], 6, v[148:149]
	v_lshl_add_u64 v[160:161], s[26:27], 0, v[148:149]
	v_mov_b32_e32 v148, v208
	v_mov_b32_e32 v149, v209
	v_mov_b32_e32 v150, v210
	v_mov_b32_e32 v151, v211
	v_mov_b32_e32 v152, v212
	v_mov_b32_e32 v153, v213
	v_mov_b32_e32 v154, v214
	v_mov_b32_e32 v155, v215
	v_mov_b32_e32 v156, v216
	v_mov_b32_e32 v157, v217
	v_mov_b32_e32 v158, v218
	v_mov_b32_e32 v159, v219
	v_mov_b32_e32 v176, v220
	v_mov_b32_e32 v177, v221
	v_mov_b32_e32 v178, v222
	v_mov_b32_e32 v179, v223
	s_waitcnt vmcnt(2)
	v_pk_add_f32 v[150:151], v[150:151], v[154:155]
	v_pk_add_f32 v[148:149], v[148:149], v[152:153]
	s_waitcnt vmcnt(0)
	v_pk_add_f32 v[158:159], v[158:159], v[178:179]
	v_pk_add_f32 v[156:157], v[156:157], v[176:177]
	v_pk_add_f32 v[150:151], v[158:159], v[150:151]
	v_pk_add_f32 v[148:149], v[156:157], v[148:149]
	s_nop 0
	v_add_f32_e32 v148, v148, v149
	v_add_f32_e32 v149, v150, v151
	v_add_f32_e32 v148, v148, v149
	v_fmamk_f32 v148, v148, 0x3a800000, v205
	v_rsq_f32_e32 v148, v148
	ds_write2st64_b32 v146, v182, v148 offset1:1

;     __device__ __forceinline__ void operator()(const f32x4 (&acc)[2][2][4][2], const Unit& u, int wr, int wc, int fr, int fq) const {
;     ...
;         const int row0 = u.pm * BM + wr * 64 + fr, col0 = u.pn * BM + wc * 32 + 8 * fq;
; #pragma unroll
;         for (int ai = 0; ai < 2; ++ai) {
;             u32x4 bx[4][2];
; #pragma unroll
;             for (int m = 0; m < 4; ++m)
; #pragma unroll
;                 for (int bj = 0; bj < 2; ++bj) bx[m][bj] = *(const u32x4*)(xb + (size_t)(row0 + ai * HALF + m * 16) * 1024 + col0 + bj * HALF);
; #pragma unroll
;             for (int m = 0; m < 4; ++m) {
;                 const int row = row0 + ai * HALF + m * 16;
;                 float ss = 0.f;
; #pragma unroll
;                 for (int bj = 0; bj < 2; ++bj) {
;                     const size_t off = (size_t)row * 1024 + col0 + bj * HALF;
;                     float b[8], v[8]; unpack8f(bx[m][bj], b);
; #pragma unroll
;                     for (int n = 0; n < 2; ++n)
; #pragma unroll
;                         for (int j = 0; j < 4; ++j) { const float t = b[n * 4 + j] + acc[ai][bj][m][n][j] * scale; v[n * 4 + j] = t; ss += t * t; }
;                     *(u32x4*)(xb + off) = pack8(v);
;                 }
;                 ss += __shfl_xor(ss, 16); ss += __shfl_xor(ss, 32);
;                 if (fq == 0) ssq[(size_t)row * 16 + u.pn * 4 + wc] = ss;
.LBB0_388:
	v_mov_b32_e32 v130, v81
	v_mov_b32_e32 v131, v208
	s_add_i32 s44, s46, s64
	v_and_b32_e32 v132, 64, v204
	v_add_u32_e32 v186, s44, v131
	v_xor_b32_e32 v131, 16, v204
	v_add_u32_e32 v132, 64, v132
	s_or_b32 s44, s48, s65
	v_cmp_lt_i32_e32 vcc, v131, v132
	v_lshl_add_u32 v184, v130, 3, s44
	v_ashrrev_i32_e32 v185, 31, v184
	v_cndmask_b32_e32 v131, v204, v131, vcc
	v_lshlrev_b32_e32 v213, 2, v131
	v_xor_b32_e32 v131, 32, v204
	v_cmp_lt_i32_e32 vcc, v131, v132
	v_lshlrev_b64 v[218:219], 1, v[184:185]
	v_ashrrev_i32_e32 v187, 31, v186
	v_cndmask_b32_e32 v131, v204, v131, vcc
	v_lshl_add_u64 v[188:189], s[30:31], 0, v[218:219]
	v_lshlrev_b64 v[220:221], 11, v[186:187]
	v_lshlrev_b32_e32 v212, 2, v131
	v_cmp_eq_u32_e32 vcc, 0, v130
	v_lshl_add_u64 v[130:131], v[188:189], 0, v[220:221]
	global_load_dwordx4 v[214:217], v[130:131], off
	global_load_dwordx4 v[154:157], v[130:131], off offset:256
	v_add_u32_e32 v198, 16, v186
	v_ashrrev_i32_e32 v199, 31, v198
	v_add_u32_e32 v194, 32, v186
	v_lshlrev_b64 v[200:201], 11, v[198:199]
	v_ashrrev_i32_e32 v195, 31, v194
	v_add_u32_e32 v190, 48, v186
	v_lshl_add_u64 v[130:131], v[188:189], 0, v[200:201]
	v_lshlrev_b64 v[196:197], 11, v[194:195]
	v_ashrrev_i32_e32 v191, 31, v190
	global_load_dwordx4 v[150:153], v[130:131], off
	global_load_dwordx4 v[146:149], v[130:131], off offset:256
	v_lshl_add_u64 v[130:131], v[188:189], 0, v[196:197]
	v_lshlrev_b64 v[192:193], 11, v[190:191]
	global_load_dwordx4 v[142:145], v[130:131], off
	global_load_dwordx4 v[138:141], v[130:131], off offset:256
	v_lshl_add_u64 v[130:131], v[188:189], 0, v[192:193]
	global_load_dwordx4 v[134:137], v[130:131], off
	s_nop 0
	global_load_dwordx4 v[130:133], v[130:131], off offset:256
	v_add_u32_e32 v230, 0x80, v186
	v_ashrrev_i32_e32 v231, 31, v230
	v_lshlrev_b64 v[230:231], 11, v[230:231]
	v_lshl_add_u64 v[230:231], v[188:189], 0, v[230:231]
	global_load_dwordx4 v[232:235], v[230:231], off
	global_load_dwordx4 v[236:239], v[230:231], off offset:256
	v_add_u32_e32 v230, 0x90, v186
	v_ashrrev_i32_e32 v231, 31, v230
	v_lshlrev_b64 v[230:231], 11, v[230:231]
	v_lshl_add_u64 v[230:231], v[188:189], 0, v[230:231]
	global_load_dwordx4 v[240:243], v[230:231], off
	global_load_dwordx4 v[244:247], v[230:231], off offset:256
	s_lshl_b32 s44, s20, 2
	s_ashr_i32 s45, s44, 31
	s_waitcnt vmcnt(0)
	v_lshlrev_b32_e32 v222, 16, v214
	v_and_b32_e32 v223, 0xffff0000, v214
	v_pk_fma_f32 v[126:127], s[12:13], v[126:127], v[222:223]
	v_lshlrev_b32_e32 v214, 16, v215
	v_and_b32_e32 v215, 0xffff0000, v215
	v_lshlrev_b32_e32 v224, 16, v216
	v_and_b32_e32 v225, 0xffff0000, v216
	v_pk_mul_f32 v[222:223], v[126:127], v[126:127]
	v_pk_fma_f32 v[128:129], s[12:13], v[128:129], v[214:215]
	v_pk_fma_f32 v[224:225], s[12:13], v[122:123], v[224:225]
	v_lshlrev_b32_e32 v122, 16, v217
	v_and_b32_e32 v123, 0xffff0000, v217
	v_pk_mul_f32 v[214:215], v[128:129], v[128:129]
	v_pk_fma_f32 v[216:217], s[12:13], v[124:125], v[122:123]
	v_cvt_pk_bf16_f32 v123, v128, v129
	v_lshlrev_b32_e32 v128, 16, v156
	v_and_b32_e32 v129, 0xffff0000, v156
	v_add_f32_e32 v156, v222, v223
	v_add_f32_e32 v156, v214, v156
	v_pk_mul_f32 v[226:227], v[224:225], v[224:225]
	v_cvt_pk_bf16_f32 v122, v126, v127
	v_lshl_add_u64 v[126:127], s[30:31], 0, v[220:221]
	v_add_f32_e32 v156, v215, v156
	v_cvt_pk_bf16_f32 v124, v224, v225
	v_cvt_pk_bf16_f32 v125, v216, v217
	v_lshl_add_u64 v[126:127], v[126:127], 0, v[218:219]
	v_add_f32_e32 v156, v226, v156
	v_pk_mul_f32 v[228:229], v[216:217], v[216:217]
	global_store_dwordx4 v[126:127], v[122:125], off
	v_add_f32_e32 v156, v227, v156
	v_add_f32_e32 v156, v228, v156
	v_lshlrev_b32_e32 v122, 16, v154
	v_and_b32_e32 v123, 0xffff0000, v154
	v_pk_fma_f32 v[118:119], s[12:13], v[118:119], v[122:123]
	v_lshlrev_b32_e32 v124, 16, v155
	v_pk_mul_f32 v[122:123], v[118:119], v[118:119]
	v_and_b32_e32 v125, 0xffff0000, v155
	v_add_f32_e32 v156, v229, v156
	v_pk_fma_f32 v[120:121], s[12:13], v[120:121], v[124:125]
	v_add_f32_e32 v122, v122, v156
	v_pk_mul_f32 v[124:125], v[120:121], v[120:121]
	v_add_f32_e32 v122, v123, v122
	v_pk_fma_f32 v[128:129], s[12:13], v[114:115], v[128:129]
	v_add_f32_e32 v122, v124, v122
	v_pk_mul_f32 v[114:115], v[128:129], v[128:129]
	v_lshlrev_b32_e32 v154, 16, v157
	v_and_b32_e32 v155, 0xffff0000, v157
	v_add_f32_e32 v122, v125, v122
	v_pk_fma_f32 v[154:155], s[12:13], v[116:117], v[154:155]
	v_add_f32_e32 v114, v114, v122
	v_pk_mul_f32 v[116:117], v[154:155], v[154:155]
	v_add_f32_e32 v114, v115, v114
	v_add_f32_e32 v114, v116, v114
	v_add_f32_e32 v122, v117, v114
	v_cvt_pk_bf16_f32 v114, v118, v119
	v_cvt_pk_bf16_f32 v115, v120, v121
	v_cvt_pk_bf16_f32 v116, v128, v129
	v_cvt_pk_bf16_f32 v117, v154, v155
	global_store_dwordx4 v[126:127], v[114:117], off offset:256
	ds_bpermute_b32 v114, v213, v122
	s_waitcnt lgkmcnt(0)
	v_add_f32_e32 v114, v122, v114
	ds_bpermute_b32 v115, v212, v114
	s_and_saveexec_b64 s[46:47], vcc
	s_cbranch_execz .LBB0_390
	v_lshlrev_b64 v[116:117], 6, v[186:187]
	v_lshl_add_u64 v[116:117], s[26:27], 0, v[116:117]
	v_lshl_add_u64 v[116:117], s[44:45], 2, v[116:117]
	s_lshl_b32 s20, s62, 2
	v_lshl_add_u64 v[116:117], v[116:117], 0, s[20:21]
	s_waitcnt lgkmcnt(0)
	v_add_f32_e32 v114, v114, v115
	global_store_dword v[116:117], v114, off

;     __device__ __forceinline__ void operator()(const f32x4 (&acc)[2][2][4][2], const Unit& u, int wr, int wc, int fr, int fq) const {
;     ...
;                 for (int bj = 0; bj < 2; ++bj) bx[m][bj] = *(const u32x4*)(xb + (size_t)(row0 + ai * HALF + m * 16) * 1024 + col0 + bj * HALF);
; #pragma unroll
;             for (int m = 0; m < 4; ++m) {
;                 const int row = row0 + ai * HALF + m * 16;
;                 float ss = 0.f;
; #pragma unroll
;                 for (int bj = 0; bj < 2; ++bj) {
;                     const size_t off = (size_t)row * 1024 + col0 + bj * HALF;
;                     float b[8], v[8]; unpack8f(bx[m][bj], b);
; #pragma unroll
;                     for (int n = 0; n < 2; ++n)
; #pragma unroll
;                         for (int j = 0; j < 4; ++j) { const float t = b[n * 4 + j] + acc[ai][bj][m][n][j] * scale; v[n * 4 + j] = t; ss += t * t; }
;                     *(u32x4*)(xb + off) = pack8(v);
;                 }
;                 ss += __shfl_xor(ss, 16); ss += __shfl_xor(ss, 32);
;                 if (fq == 0) ssq[(size_t)row * 16 + u.pn * 4 + wc] = ss;
.LBB0_396:
	s_or_b64 exec, exec, s[46:47]
	v_add_u32_e32 v102, 0x80, v186
	v_ashrrev_i32_e32 v103, 31, v102
	v_lshlrev_b64 v[112:113], 11, v[102:103]
	s_waitcnt lgkmcnt(0)
	v_lshl_add_u64 v[64:65], v[188:189], 0, v[112:113]
	v_mov_b32_e32 v104, v232
	v_mov_b32_e32 v105, v233
	v_mov_b32_e32 v106, v234
	v_mov_b32_e32 v107, v235
	v_mov_b32_e32 v108, v236
	v_mov_b32_e32 v109, v237
	v_mov_b32_e32 v110, v238
	v_mov_b32_e32 v111, v239
	v_add_u32_e32 v98, 0x90, v186
	v_ashrrev_i32_e32 v99, 31, v98
	v_add_u32_e32 v94, 0xa0, v186
	v_lshlrev_b64 v[100:101], 11, v[98:99]
	v_ashrrev_i32_e32 v95, 31, v94
	v_add_u32_e32 v90, 0xb0, v186
	v_lshl_add_u64 v[64:65], v[188:189], 0, v[100:101]
	v_lshlrev_b64 v[96:97], 11, v[94:95]
	v_ashrrev_i32_e32 v91, 31, v90
	v_mov_b32_e32 v86, v240
	v_mov_b32_e32 v87, v241
	v_mov_b32_e32 v88, v242
	v_mov_b32_e32 v89, v243
	v_mov_b32_e32 v82, v244
	v_mov_b32_e32 v83, v245
	v_mov_b32_e32 v84, v246
	v_mov_b32_e32 v85, v247
	v_lshl_add_u64 v[64:65], v[188:189], 0, v[96:97]
	v_lshlrev_b64 v[92:93], 11, v[90:91]
	global_load_dwordx4 v[76:79], v[64:65], off
	global_load_dwordx4 v[72:75], v[64:65], off offset:256
	v_lshl_add_u64 v[64:65], v[188:189], 0, v[92:93]
	global_load_dwordx4 v[68:71], v[64:65], off
	s_nop 0
	global_load_dwordx4 v[64:67], v[64:65], off offset:256
	s_waitcnt vmcnt(7)
	v_lshlrev_b32_e32 v114, 16, v104
	v_and_b32_e32 v115, 0xffff0000, v104
	v_lshlrev_b32_e32 v116, 16, v106
	v_and_b32_e32 v117, 0xffff0000, v106
	v_pk_fma_f32 v[60:61], s[12:13], v[60:61], v[114:115]
	v_lshlrev_b32_e32 v104, 16, v105
	v_and_b32_e32 v105, 0xffff0000, v105
	v_pk_fma_f32 v[116:117], s[12:13], v[56:57], v[116:117]
	v_lshlrev_b32_e32 v56, 16, v107
	v_and_b32_e32 v57, 0xffff0000, v107
	v_pk_mul_f32 v[114:115], v[60:61], v[60:61]
	v_pk_fma_f32 v[62:63], s[12:13], v[62:63], v[104:105]
	v_pk_fma_f32 v[106:107], s[12:13], v[58:59], v[56:57]
	v_cvt_pk_bf16_f32 v56, v60, v61
	v_lshl_add_u64 v[60:61], s[30:31], 0, v[112:113]
	v_cvt_pk_bf16_f32 v57, v62, v63
	v_cvt_pk_bf16_f32 v58, v116, v117
	v_cvt_pk_bf16_f32 v59, v106, v107
	v_lshl_add_u64 v[60:61], v[184:185], 1, v[60:61]
	v_pk_mul_f32 v[104:105], v[62:63], v[62:63]
	global_store_dwordx4 v[60:61], v[56:59], off
	v_pk_mul_f32 v[118:119], v[116:117], v[116:117]
	v_pk_mul_f32 v[120:121], v[106:107], v[106:107]
	s_waitcnt vmcnt(7)
	v_lshlrev_b32_e32 v56, 16, v108
	v_and_b32_e32 v57, 0xffff0000, v108
	v_add_f32_e32 v108, v114, v115
	v_add_f32_e32 v104, v104, v108
	v_add_f32_e32 v104, v105, v104
	v_add_f32_e32 v104, v118, v104
	v_add_f32_e32 v104, v119, v104
	v_pk_fma_f32 v[52:53], s[12:13], v[52:53], v[56:57]
	v_add_f32_e32 v104, v120, v104
	v_pk_mul_f32 v[56:57], v[52:53], v[52:53]
	v_lshlrev_b32_e32 v58, 16, v109
	v_and_b32_e32 v59, 0xffff0000, v109
	v_add_f32_e32 v104, v121, v104
	v_pk_fma_f32 v[54:55], s[12:13], v[54:55], v[58:59]
	v_add_f32_e32 v56, v56, v104
	v_pk_mul_f32 v[58:59], v[54:55], v[54:55]
	v_lshlrev_b32_e32 v62, 16, v110
	v_and_b32_e32 v63, 0xffff0000, v110
	v_add_f32_e32 v56, v57, v56
	v_pk_fma_f32 v[62:63], s[12:13], v[48:49], v[62:63]
	v_add_f32_e32 v56, v58, v56
	v_pk_mul_f32 v[48:49], v[62:63], v[62:63]
	v_lshlrev_b32_e32 v106, 16, v111
	v_and_b32_e32 v107, 0xffff0000, v111
	v_add_f32_e32 v56, v59, v56
	v_pk_fma_f32 v[106:107], s[12:13], v[50:51], v[106:107]
	v_add_f32_e32 v48, v48, v56
	v_pk_mul_f32 v[50:51], v[106:107], v[106:107]
	v_add_f32_e32 v48, v49, v48
	v_add_f32_e32 v48, v50, v48
	v_add_f32_e32 v56, v51, v48
	v_cvt_pk_bf16_f32 v48, v52, v53
	v_cvt_pk_bf16_f32 v49, v54, v55
	v_cvt_pk_bf16_f32 v50, v62, v63
	v_cvt_pk_bf16_f32 v51, v106, v107
	global_store_dwordx4 v[60:61], v[48:51], off offset:256
	ds_bpermute_b32 v48, v213, v56
	s_waitcnt lgkmcnt(0)
	v_add_f32_e32 v48, v56, v48
	ds_bpermute_b32 v49, v212, v48
	s_and_saveexec_b64 s[46:47], vcc
	s_cbranch_execz .LBB0_398
	v_lshlrev_b64 v[50:51], 6, v[102:103]
	v_lshl_add_u64 v[50:51], s[26:27], 0, v[50:51]
	v_lshl_add_u64 v[50:51], s[44:45], 2, v[50:51]
	s_lshl_b32 s20, s62, 2
	v_lshl_add_u64 v[50:51], v[50:51], 0, s[20:21]
	s_waitcnt lgkmcnt(0)
	v_add_f32_e32 v48, v48, v49
	global_store_dword v[50:51], v48, off
